# P4 epilogue: touch next x row-group right after issuing current group loads (prefetch), waits recounted
# baseline (speedup 1.0000x reference)
.LBB0_666:
	s_lshl_b32 s10, s6, 8
	s_add_i32 s1, s10, s38
	s_lshl_b32 s0, s7, 5
	v_or_b32_e32 v130, s1, v145
	s_lshl_b32 s1, s8, 8
	s_or_b32 s0, s1, s0
	v_lshrrev_b32_e32 v128, 2, v144
	v_ashrrev_i32_e32 v131, 31, v130
	v_and_or_b32 v128, v128, 12, s0
	v_lshlrev_b64 v[132:133], 13, v[130:131]
	v_ashrrev_i32_e32 v129, 31, v128
	v_lshl_add_u64 v[132:133], s[44:45], 0, v[132:133]
	v_lshl_add_u64 v[148:149], v[128:129], 2, v[132:133]
	s_barrier
	global_load_dwordx4 v[132:135], v[148:149], off nt
	global_load_dwordx4 v[136:139], v[148:149], off offset:64 nt
	global_load_dwordx4 v[140:143], v[148:149], off offset:512 nt
	global_load_dwordx4 v[150:153], v[148:149], off offset:576 nt
	v_mov_b32_e32 v178, v148
	v_mov_b32_e32 v179, v149
	s_mov_b32 s20, 0x20000
	s_mov_b32 s21, 0
	v_lshl_add_u64 v[180:181], v[178:179], 0, s[20:21]
	global_load_dword v182, v[180:181], off nt
	global_load_dword v183, v[180:181], off offset:64 nt
	global_load_dword v184, v[180:181], off offset:512 nt
	global_load_dword v185, v[180:181], off offset:576 nt
	v_mbcnt_hi_u32_b32 v148, -1, v169
	v_and_b32_e32 v145, 64, v148
	v_and_b32_e32 v147, 63, v144
	v_xor_b32_e32 v144, 16, v148
	v_add_u32_e32 v154, 64, v145
	v_cmp_lt_i32_e32 vcc, v144, v154
	s_lshl_b32 s2, s7, 2
	s_add_i32 s4, s2, 0
	v_cndmask_b32_e32 v144, v148, v144, vcc
	v_lshlrev_b32_e32 v149, 2, v144
	v_cmp_gt_u32_e64 s[0:1], 16, v147
	s_waitcnt vmcnt(4)
	v_pk_add_f32 v[126:127], v[126:127], v[134:135]
	v_pk_add_f32 v[124:125], v[124:125], v[132:133]
	v_pk_add_f32 v[122:123], v[122:123], v[138:139]
	v_pk_add_f32 v[120:121], v[120:121], v[136:137]
	v_pk_add_f32 v[118:119], v[118:119], v[142:143]
	v_pk_add_f32 v[116:117], v[116:117], v[140:141]
	v_pk_mul_f32 v[132:133], v[126:127], v[126:127]
	v_pk_mul_f32 v[134:135], v[124:125], v[124:125]
	v_pk_mul_f32 v[136:137], v[122:123], v[122:123]
	v_pk_mul_f32 v[138:139], v[120:121], v[120:121]
	v_pk_add_f32 v[114:115], v[114:115], v[152:153]
	v_pk_add_f32 v[112:113], v[112:113], v[150:151]
	v_pk_mul_f32 v[140:141], v[118:119], v[118:119]
	v_pk_mul_f32 v[142:143], v[116:117], v[116:117]
	v_add_f32_e32 v136, v136, v137
	v_add_f32_e32 v137, v138, v139
	v_add_f32_e32 v132, v132, v133
	v_add_f32_e32 v133, v134, v135
	v_pk_mul_f32 v[144:145], v[114:115], v[114:115]
	v_pk_mul_f32 v[150:151], v[112:113], v[112:113]
	v_add_f32_e32 v134, v140, v141
	v_add_f32_e32 v135, v142, v143
	v_add_f32_e32 v136, v137, v136
	v_add_f32_e32 v132, v133, v132
	v_add_f32_e32 v138, v144, v145
	v_add_f32_e32 v139, v150, v151
	v_add_f32_e32 v133, v135, v134
	v_add_f32_e32 v132, v132, v136
	v_add_f32_e32 v132, v132, v133
	v_add_f32_e32 v133, v139, v138
	v_add_f32_e32 v132, v132, v133
	ds_bpermute_b32 v133, v149, v132
	v_xor_b32_e32 v134, 32, v148
	v_cmp_lt_i32_e32 vcc, v134, v154
	v_lshl_add_u32 v150, v146, 4, s4
	s_waitcnt lgkmcnt(0)
	v_add_f32_e32 v132, v132, v133
	v_cndmask_b32_e32 v134, v148, v134, vcc
	v_lshlrev_b32_e32 v151, 2, v134
	ds_bpermute_b32 v133, v151, v132
	s_and_saveexec_b64 s[2:3], s[0:1]
	s_cbranch_execz .LBB0_668
	s_waitcnt lgkmcnt(0)
	v_add_f32_e32 v132, v132, v133
	ds_write_b32 v150, v132
.LBB0_668:
	s_or_b64 exec, exec, s[2:3]
	v_or_b32_e32 v132, 16, v130
	s_waitcnt lgkmcnt(0)
	v_ashrrev_i32_e32 v133, 31, v132
	v_lshlrev_b64 v[132:133], 13, v[132:133]
	v_lshl_add_u64 v[132:133], s[44:45], 0, v[132:133]
	v_lshl_add_u64 v[144:145], v[128:129], 2, v[132:133]
	global_load_dwordx4 v[132:135], v[144:145], off nt
	global_load_dwordx4 v[136:139], v[144:145], off offset:64 nt
	global_load_dwordx4 v[140:143], v[144:145], off offset:512 nt
	global_load_dwordx4 v[152:155], v[144:145], off offset:576 nt
	s_mov_b32 s20, 0x40000
	s_mov_b32 s21, 0
	v_lshl_add_u64 v[180:181], v[178:179], 0, s[20:21]
	global_load_dword v182, v[180:181], off nt
	global_load_dword v183, v[180:181], off offset:64 nt
	global_load_dword v184, v[180:181], off offset:512 nt
	global_load_dword v185, v[180:181], off offset:576 nt
	s_waitcnt vmcnt(7)
	v_pk_add_f32 v[110:111], v[110:111], v[134:135]
	v_pk_add_f32 v[108:109], v[108:109], v[132:133]
	s_waitcnt vmcnt(6)
	v_pk_add_f32 v[106:107], v[106:107], v[138:139]
	v_pk_add_f32 v[104:105], v[104:105], v[136:137]
	s_waitcnt vmcnt(5)
	v_pk_add_f32 v[102:103], v[102:103], v[142:143]
	v_pk_add_f32 v[100:101], v[100:101], v[140:141]
	v_pk_mul_f32 v[132:133], v[110:111], v[110:111]
	v_pk_mul_f32 v[134:135], v[108:109], v[108:109]
	v_pk_mul_f32 v[136:137], v[106:107], v[106:107]
	v_pk_mul_f32 v[138:139], v[104:105], v[104:105]
	s_waitcnt vmcnt(4)
	v_pk_add_f32 v[98:99], v[98:99], v[154:155]
	v_pk_add_f32 v[96:97], v[96:97], v[152:153]
	v_pk_mul_f32 v[140:141], v[102:103], v[102:103]
	v_pk_mul_f32 v[142:143], v[100:101], v[100:101]
	v_add_f32_e32 v136, v136, v137
	v_add_f32_e32 v137, v138, v139
	v_add_f32_e32 v132, v132, v133
	v_add_f32_e32 v133, v134, v135
	v_pk_mul_f32 v[144:145], v[98:99], v[98:99]
	v_pk_mul_f32 v[152:153], v[96:97], v[96:97]
	v_add_f32_e32 v134, v140, v141
	v_add_f32_e32 v135, v142, v143
	v_add_f32_e32 v136, v137, v136
	v_add_f32_e32 v132, v133, v132
	v_add_f32_e32 v138, v144, v145
	v_add_f32_e32 v139, v152, v153
	v_add_f32_e32 v133, v135, v134
	v_add_f32_e32 v132, v132, v136
	v_add_f32_e32 v132, v132, v133
	v_add_f32_e32 v133, v139, v138
	v_add_f32_e32 v132, v132, v133
	ds_bpermute_b32 v133, v149, v132
	s_waitcnt lgkmcnt(0)
	v_add_f32_e32 v132, v132, v133
	ds_bpermute_b32 v133, v151, v132
	s_and_saveexec_b64 s[2:3], s[0:1]
	s_cbranch_execz .LBB0_670
	s_waitcnt lgkmcnt(0)
	v_add_f32_e32 v132, v132, v133
	ds_write_b32 v150, v132 offset:256
.LBB0_670:
	s_or_b64 exec, exec, s[2:3]
	v_or_b32_e32 v132, 32, v130
	s_waitcnt lgkmcnt(0)
	v_ashrrev_i32_e32 v133, 31, v132
	v_lshlrev_b64 v[132:133], 13, v[132:133]
	v_lshl_add_u64 v[132:133], s[44:45], 0, v[132:133]
	v_lshl_add_u64 v[144:145], v[128:129], 2, v[132:133]
	global_load_dwordx4 v[132:135], v[144:145], off nt
	global_load_dwordx4 v[136:139], v[144:145], off offset:64 nt
	global_load_dwordx4 v[140:143], v[144:145], off offset:512 nt
	global_load_dwordx4 v[152:155], v[144:145], off offset:576 nt
	s_mov_b32 s20, 0x60000
	s_mov_b32 s21, 0
	v_lshl_add_u64 v[180:181], v[178:179], 0, s[20:21]
	global_load_dword v182, v[180:181], off nt
	global_load_dword v183, v[180:181], off offset:64 nt
	global_load_dword v184, v[180:181], off offset:512 nt
	global_load_dword v185, v[180:181], off offset:576 nt
	s_waitcnt vmcnt(7)
	v_pk_add_f32 v[94:95], v[94:95], v[134:135]
	v_pk_add_f32 v[92:93], v[92:93], v[132:133]
	s_waitcnt vmcnt(6)
	v_pk_add_f32 v[90:91], v[90:91], v[138:139]
	v_pk_add_f32 v[88:89], v[88:89], v[136:137]
	s_waitcnt vmcnt(5)
	v_pk_add_f32 v[86:87], v[86:87], v[142:143]
	v_pk_add_f32 v[84:85], v[84:85], v[140:141]
	v_pk_mul_f32 v[132:133], v[94:95], v[94:95]
	v_pk_mul_f32 v[134:135], v[92:93], v[92:93]
	v_pk_mul_f32 v[136:137], v[90:91], v[90:91]
	v_pk_mul_f32 v[138:139], v[88:89], v[88:89]
	s_waitcnt vmcnt(4)
	v_pk_add_f32 v[82:83], v[82:83], v[154:155]
	v_pk_add_f32 v[80:81], v[80:81], v[152:153]
	v_pk_mul_f32 v[140:141], v[86:87], v[86:87]
	v_pk_mul_f32 v[142:143], v[84:85], v[84:85]
	v_add_f32_e32 v136, v136, v137
	v_add_f32_e32 v137, v138, v139
	v_add_f32_e32 v132, v132, v133
	v_add_f32_e32 v133, v134, v135
	v_pk_mul_f32 v[144:145], v[82:83], v[82:83]
	v_pk_mul_f32 v[152:153], v[80:81], v[80:81]
	v_add_f32_e32 v134, v140, v141
	v_add_f32_e32 v135, v142, v143
	v_add_f32_e32 v136, v137, v136
	v_add_f32_e32 v132, v133, v132
	v_add_f32_e32 v138, v144, v145
	v_add_f32_e32 v139, v152, v153
	v_add_f32_e32 v133, v135, v134
	v_add_f32_e32 v132, v132, v136
	v_add_f32_e32 v132, v132, v133
	v_add_f32_e32 v133, v139, v138
	v_add_f32_e32 v132, v132, v133
	ds_bpermute_b32 v133, v149, v132
	s_waitcnt lgkmcnt(0)
	v_add_f32_e32 v132, v132, v133
	ds_bpermute_b32 v133, v151, v132
	s_and_saveexec_b64 s[2:3], s[0:1]
	s_cbranch_execz .LBB0_672
	s_waitcnt lgkmcnt(0)
	v_add_f32_e32 v132, v132, v133
	ds_write_b32 v150, v132 offset:512
.LBB0_672:
	s_or_b64 exec, exec, s[2:3]
	v_or_b32_e32 v132, 48, v130
	s_waitcnt lgkmcnt(0)
	v_ashrrev_i32_e32 v133, 31, v132
	v_lshlrev_b64 v[132:133], 13, v[132:133]
	v_lshl_add_u64 v[132:133], s[44:45], 0, v[132:133]
	v_lshl_add_u64 v[144:145], v[128:129], 2, v[132:133]
	global_load_dwordx4 v[132:135], v[144:145], off nt
	global_load_dwordx4 v[136:139], v[144:145], off offset:64 nt
	global_load_dwordx4 v[140:143], v[144:145], off offset:512 nt
	global_load_dwordx4 v[152:155], v[144:145], off offset:576 nt
	s_mov_b32 s20, 0x100000
	s_mov_b32 s21, 0
	v_lshl_add_u64 v[180:181], v[178:179], 0, s[20:21]
	global_load_dword v182, v[180:181], off nt
	global_load_dword v183, v[180:181], off offset:64 nt
	global_load_dword v184, v[180:181], off offset:512 nt
	global_load_dword v185, v[180:181], off offset:576 nt
	s_waitcnt vmcnt(7)
	v_pk_add_f32 v[78:79], v[78:79], v[134:135]
	v_pk_add_f32 v[76:77], v[76:77], v[132:133]
	s_waitcnt vmcnt(6)
	v_pk_add_f32 v[74:75], v[74:75], v[138:139]
	v_pk_add_f32 v[72:73], v[72:73], v[136:137]
	s_waitcnt vmcnt(5)
	v_pk_add_f32 v[70:71], v[70:71], v[142:143]
	v_pk_add_f32 v[68:69], v[68:69], v[140:141]
	v_pk_mul_f32 v[132:133], v[78:79], v[78:79]
	v_pk_mul_f32 v[134:135], v[76:77], v[76:77]
	v_pk_mul_f32 v[136:137], v[74:75], v[74:75]
	v_pk_mul_f32 v[138:139], v[72:73], v[72:73]
	s_waitcnt vmcnt(4)
	v_pk_add_f32 v[66:67], v[66:67], v[154:155]
	v_pk_add_f32 v[64:65], v[64:65], v[152:153]
	v_pk_mul_f32 v[140:141], v[70:71], v[70:71]
	v_pk_mul_f32 v[142:143], v[68:69], v[68:69]
	v_add_f32_e32 v136, v136, v137
	v_add_f32_e32 v137, v138, v139
	v_add_f32_e32 v132, v132, v133
	v_add_f32_e32 v133, v134, v135
	v_pk_mul_f32 v[144:145], v[66:67], v[66:67]
	v_pk_mul_f32 v[152:153], v[64:65], v[64:65]
	v_add_f32_e32 v134, v140, v141
	v_add_f32_e32 v135, v142, v143
	v_add_f32_e32 v136, v137, v136
	v_add_f32_e32 v132, v133, v132
	v_add_f32_e32 v138, v144, v145
	v_add_f32_e32 v139, v152, v153
	v_add_f32_e32 v133, v135, v134
	v_add_f32_e32 v132, v132, v136
	v_add_f32_e32 v132, v132, v133
	v_add_f32_e32 v133, v139, v138
	v_add_f32_e32 v132, v132, v133
	ds_bpermute_b32 v133, v149, v132
	s_waitcnt lgkmcnt(0)
	v_add_f32_e32 v132, v132, v133
	ds_bpermute_b32 v133, v151, v132
	s_and_saveexec_b64 s[2:3], s[0:1]
	s_cbranch_execz .LBB0_674
	s_waitcnt lgkmcnt(0)
	v_add_f32_e32 v132, v132, v133
	ds_write_b32 v150, v132 offset:768
.LBB0_674:
	s_or_b64 exec, exec, s[2:3]
	s_waitcnt lgkmcnt(0)
	v_lshlrev_b64 v[132:133], 13, v[130:131]
	v_lshl_add_u64 v[132:133], s[44:45], 0, v[132:133]
	v_lshl_add_u64 v[132:133], v[128:129], 2, v[132:133]
	s_mov_b64 s[2:3], 0x100000
	v_lshl_add_u64 v[152:153], v[132:133], 0, s[2:3]
	v_add_co_u32_e32 v142, vcc, 0x100000, v132
	global_load_dwordx4 v[134:137], v[152:153], off offset:64 nt
	global_load_dwordx4 v[138:141], v[152:153], off offset:512 nt
	v_addc_co_u32_e32 v143, vcc, 0, v133, vcc
	global_load_dwordx4 v[142:145], v[142:143], off nt
	s_nop 0
	global_load_dwordx4 v[152:155], v[152:153], off offset:576 nt
	s_mov_b32 s20, 0x120000
	s_mov_b32 s21, 0
	v_lshl_add_u64 v[180:181], v[178:179], 0, s[20:21]
	global_load_dword v182, v[180:181], off nt
	global_load_dword v183, v[180:181], off offset:64 nt
	global_load_dword v184, v[180:181], off offset:512 nt
	global_load_dword v185, v[180:181], off offset:576 nt
	v_add_u32_e32 v148, 0x80, v146
	s_waitcnt vmcnt(7)
	v_pk_add_f32 v[58:59], v[58:59], v[136:137]
	v_pk_add_f32 v[56:57], v[56:57], v[134:135]
	s_waitcnt vmcnt(6)
	v_pk_add_f32 v[54:55], v[54:55], v[140:141]
	s_waitcnt vmcnt(5)
	v_pk_add_f32 v[62:63], v[62:63], v[144:145]
	v_pk_add_f32 v[60:61], v[60:61], v[142:143]
	v_pk_add_f32 v[52:53], v[52:53], v[138:139]
	v_pk_mul_f32 v[134:135], v[58:59], v[58:59]
	v_pk_mul_f32 v[136:137], v[56:57], v[56:57]
	v_pk_mul_f32 v[138:139], v[54:55], v[54:55]
	v_pk_mul_f32 v[142:143], v[62:63], v[62:63]
	v_pk_mul_f32 v[144:145], v[60:61], v[60:61]
	v_pk_mul_f32 v[140:141], v[52:53], v[52:53]
	s_waitcnt vmcnt(4)
	v_pk_add_f32 v[50:51], v[50:51], v[154:155]
	v_pk_add_f32 v[48:49], v[48:49], v[152:153]
	v_add_f32_e32 v134, v134, v135
	v_add_f32_e32 v135, v136, v137
	v_add_f32_e32 v136, v138, v139
	v_add_f32_e32 v138, v142, v143
	v_add_f32_e32 v139, v144, v145
	v_pk_mul_f32 v[152:153], v[50:51], v[50:51]
	v_pk_mul_f32 v[154:155], v[48:49], v[48:49]
	v_add_f32_e32 v137, v140, v141
	v_add_f32_e32 v134, v135, v134
	v_add_f32_e32 v138, v139, v138
	v_add_f32_e32 v135, v137, v136
	v_add_f32_e32 v136, v152, v153
	v_add_f32_e32 v137, v154, v155
	v_add_f32_e32 v134, v138, v134
	v_add_f32_e32 v134, v134, v135
	v_add_f32_e32 v135, v137, v136
	v_add_f32_e32 v134, v134, v135
	ds_bpermute_b32 v135, v149, v134
	s_waitcnt lgkmcnt(0)
	v_add_f32_e32 v134, v134, v135
	ds_bpermute_b32 v135, v151, v134
	s_and_saveexec_b64 s[2:3], s[0:1]
	s_cbranch_execz .LBB0_676
	v_lshl_add_u32 v136, v148, 4, s4
	s_waitcnt lgkmcnt(0)
	v_add_f32_e32 v134, v134, v135
	ds_write_b32 v136, v134
.LBB0_676:
	s_or_b64 exec, exec, s[2:3]
	v_add_co_u32_e32 v134, vcc, 0x120000, v132
	s_mov_b64 s[2:3], 0x120000
	s_waitcnt lgkmcnt(0)
	v_addc_co_u32_e32 v135, vcc, 0, v133, vcc
	global_load_dwordx4 v[134:137], v[134:135], off nt
	v_lshl_add_u64 v[132:133], v[132:133], 0, s[2:3]
	global_load_dwordx4 v[138:141], v[132:133], off offset:64 nt
	global_load_dwordx4 v[142:145], v[132:133], off offset:512 nt
	global_load_dwordx4 v[152:155], v[132:133], off offset:576 nt
	s_mov_b32 s20, 0x140000
	s_mov_b32 s21, 0
	v_lshl_add_u64 v[180:181], v[178:179], 0, s[20:21]
	global_load_dword v182, v[180:181], off nt
	global_load_dword v183, v[180:181], off offset:64 nt
	global_load_dword v184, v[180:181], off offset:512 nt
	global_load_dword v185, v[180:181], off offset:576 nt
	s_waitcnt vmcnt(6)
	v_pk_add_f32 v[42:43], v[42:43], v[140:141]
	v_pk_add_f32 v[46:47], v[46:47], v[136:137]
	v_pk_add_f32 v[44:45], v[44:45], v[134:135]
	v_pk_add_f32 v[40:41], v[40:41], v[138:139]
	s_waitcnt vmcnt(5)
	v_pk_add_f32 v[38:39], v[38:39], v[144:145]
	v_pk_add_f32 v[36:37], v[36:37], v[142:143]
	v_pk_mul_f32 v[132:133], v[46:47], v[46:47]
	v_pk_mul_f32 v[134:135], v[44:45], v[44:45]
	v_pk_mul_f32 v[136:137], v[42:43], v[42:43]
	v_pk_mul_f32 v[138:139], v[40:41], v[40:41]
	s_waitcnt vmcnt(4)
	v_pk_add_f32 v[34:35], v[34:35], v[154:155]
	v_pk_add_f32 v[32:33], v[32:33], v[152:153]
	v_pk_mul_f32 v[140:141], v[38:39], v[38:39]
	v_pk_mul_f32 v[142:143], v[36:37], v[36:37]
	v_add_f32_e32 v132, v132, v133
	v_add_f32_e32 v133, v134, v135
	v_add_f32_e32 v134, v136, v137
	v_add_f32_e32 v135, v138, v139
	v_pk_mul_f32 v[144:145], v[34:35], v[34:35]
	v_pk_mul_f32 v[152:153], v[32:33], v[32:33]
	v_add_f32_e32 v136, v140, v141
	v_add_f32_e32 v137, v142, v143
	v_add_f32_e32 v132, v133, v132
	v_add_f32_e32 v133, v135, v134
	v_add_f32_e32 v138, v144, v145
	v_add_f32_e32 v139, v152, v153
	v_add_f32_e32 v134, v137, v136
	v_add_f32_e32 v132, v132, v133
	v_add_f32_e32 v132, v132, v134
	v_add_f32_e32 v133, v139, v138
	v_add_f32_e32 v132, v132, v133
	ds_bpermute_b32 v133, v149, v132
	s_waitcnt lgkmcnt(0)
	v_add_f32_e32 v132, v132, v133
	ds_bpermute_b32 v133, v151, v132
	s_and_saveexec_b64 s[2:3], s[0:1]
	s_cbranch_execz .LBB0_678
	s_waitcnt lgkmcnt(0)
	v_add_f32_e32 v132, v132, v133
	ds_write_b32 v150, v132 offset:2304
.LBB0_678:
	s_or_b64 exec, exec, s[2:3]
	v_lshlrev_b64 v[130:131], 13, v[130:131]
	v_lshl_add_u64 v[130:131], s[44:45], 0, v[130:131]
	v_lshl_add_u64 v[130:131], v[128:129], 2, v[130:131]
	s_mov_b64 s[2:3], 0x140000
	v_lshl_add_u64 v[144:145], v[130:131], 0, s[2:3]
	v_add_co_u32_e32 v140, vcc, 0x140000, v130
	s_waitcnt lgkmcnt(0)
	global_load_dwordx4 v[132:135], v[144:145], off offset:64 nt
	global_load_dwordx4 v[136:139], v[144:145], off offset:512 nt
	v_addc_co_u32_e32 v141, vcc, 0, v131, vcc
	global_load_dwordx4 v[140:143], v[140:141], off nt
	s_nop 0
	global_load_dwordx4 v[152:155], v[144:145], off offset:576 nt
	s_mov_b32 s20, 0x160000
	s_mov_b32 s21, 0
	v_lshl_add_u64 v[180:181], v[178:179], 0, s[20:21]
	global_load_dword v182, v[180:181], off nt
	global_load_dword v183, v[180:181], off offset:64 nt
	global_load_dword v184, v[180:181], off offset:512 nt
	global_load_dword v185, v[180:181], off offset:576 nt
	s_waitcnt vmcnt(7)
	v_pk_add_f32 v[26:27], v[26:27], v[134:135]
	v_pk_add_f32 v[24:25], v[24:25], v[132:133]
	s_waitcnt vmcnt(6)
	v_pk_add_f32 v[22:23], v[22:23], v[138:139]
	s_waitcnt vmcnt(5)
	v_pk_add_f32 v[30:31], v[30:31], v[142:143]
	v_pk_add_f32 v[28:29], v[28:29], v[140:141]
	v_pk_add_f32 v[20:21], v[20:21], v[136:137]
	v_pk_mul_f32 v[132:133], v[26:27], v[26:27]
	v_pk_mul_f32 v[134:135], v[24:25], v[24:25]
	v_pk_mul_f32 v[136:137], v[22:23], v[22:23]
	v_pk_mul_f32 v[140:141], v[30:31], v[30:31]
	v_pk_mul_f32 v[142:143], v[28:29], v[28:29]
	v_pk_mul_f32 v[138:139], v[20:21], v[20:21]
	s_waitcnt vmcnt(4)
	v_pk_add_f32 v[18:19], v[18:19], v[154:155]
	v_pk_add_f32 v[16:17], v[16:17], v[152:153]
	v_add_f32_e32 v132, v132, v133
	v_add_f32_e32 v133, v134, v135
	v_add_f32_e32 v134, v136, v137
	v_add_f32_e32 v136, v140, v141
	v_add_f32_e32 v137, v142, v143
	v_pk_mul_f32 v[144:145], v[18:19], v[18:19]
	v_pk_mul_f32 v[152:153], v[16:17], v[16:17]
	v_add_f32_e32 v135, v138, v139
	v_add_f32_e32 v132, v133, v132
	v_add_f32_e32 v136, v137, v136
	v_add_f32_e32 v133, v135, v134
	v_add_f32_e32 v134, v144, v145
	v_add_f32_e32 v135, v152, v153
	v_add_f32_e32 v132, v136, v132
	v_add_f32_e32 v132, v132, v133
	v_add_f32_e32 v133, v135, v134
	v_add_f32_e32 v132, v132, v133
	ds_bpermute_b32 v133, v149, v132
	s_waitcnt lgkmcnt(0)
	v_add_f32_e32 v132, v132, v133
	ds_bpermute_b32 v133, v151, v132
	s_and_saveexec_b64 s[2:3], s[0:1]
	s_cbranch_execz .LBB0_680
	s_waitcnt lgkmcnt(0)
	v_add_f32_e32 v132, v132, v133
	ds_write_b32 v150, v132 offset:2560
